# carry: the LDS exchange tile of the state uses a 68-dword row stride (no 16-way bank conflict on the fragment reads, no 4-way on the writes)
# speedup vs baseline: 1.0114x; 1.0114x over previous
; __device__ __forceinline__ int pg8_opaque_lane() { unsigned m = ~0u; asm volatile("" : "+s"(m)); return (int)__builtin_amdgcn_mbcnt_hi(m, __builtin_amdgcn_mbcnt_lo(m, 0u)); }
; #define LAS __attribute__((address_space(3)))
; #define CARRY_LOAD(Q, C) do { const float* pc_ = PC + cb0 + (size_t)(C) * 4096 + g4 * 64 + ct * 16 + fr; \
;                 _Pragma("unroll") for (int kk = 0; kk < 16; ++kk) pr[Q][kk] = pc_[kk * 256]; \
;                 const float* lc_ = LC + cb0 + (size_t)(C) * 4096 + (size_t)(r0 + g4 * 4) * 64 + ct * 16 + fr; \
;                 lr[Q] = (f32x4c){lc_[0], lc_[64], lc_[128], lc_[192]}; } while (0)
; __device__ __forceinline__ void even_carry(const Params& p, int j, LAS unsigned char* lds, const int wave_s) {
;     unsigned char* ws = p.ws;
;     const float* LC = (const float*)(ws + WS_LC); const float* PC = (const float*)(ws + WS_PC); float* SST = (float*)(ws + WS_SST);
;     LAS float* Ss = (LAS float*)lds;
;     const int lane = pg8_opaque_lane(), fr = lane & 15, g4 = lane >> 4, ct = wave_s;
;     for (int unit = blockIdx.x; unit < 256; unit += gridDim.x) {
;         const int bh = unit >> 2, r0 = (unit & 3) * 16;
;         const size_t cb0 = (size_t)(bh * NCH) * 4096;
;         if (ct < 4) {
;             float pr[4][16]; f32x4c lr[4];
;     ...
;             CARRY_LOAD(0, 0); CARRY_LOAD(1, 1); CARRY_LOAD(2, 2); CARRY_LOAD(3, 3);
;             f32x4c d = (f32x4c){0.f, 0.f, 0.f, 0.f};
;             for (int c4 = 0; c4 < NCH; c4 += 4) {
; #pragma unroll
;                 for (int q = 0; q < 4; ++q) {
;                     const int c = c4 + q;
;                     float* sst = SST + cb0 + (size_t)c * 4096 + (size_t)(r0 + g4 * 4) * 64 + ct * 16 + fr;
;                     LAS float* sb = Ss + (c & 1) * 1024;
; #pragma unroll
;                     for (int r = 0; r < 4; ++r) { sst[r * 64] = d[r]; sb[(g4 * 4 + r) * 64 + ct * 16 + fr] = d[r]; }
.LBB0_1427:
	v_readlane_b32 s2, v253, 37
	v_readlane_b32 s3, v253, 38
	s_mov_b32 s0, -1
	s_andn2_b64 vcc, exec, s[2:3]
	s_waitcnt vmcnt(17) lgkmcnt(0)
	v_cndmask_b32_e64 v0, 0, 1, s[2:3]
	v_cmp_ne_u32_e64 s[36:37], 1, v0
	s_barrier
	s_cbranch_vccnz .LBB0_1444
	v_mbcnt_lo_u32_b32 v0, s0, 0
	v_mbcnt_hi_u32_b32 v0, s0, v0
	v_and_b32_e32 v20, 15, v0
	v_lshrrev_b32_e32 v1, 4, v0
	v_lshlrev_b32_e32 v22, 2, v20
	v_readlane_b32 s0, v253, 54
	v_readlane_b32 s2, v255, 1
	v_lshlrev_b32_e32 v0, 6, v1
	v_lshlrev_b32_e32 v21, 2, v1
	v_mul_u32_u24_e32 v2, 0x110, v20
	v_add_u32_e32 v3, s0, v22
	v_mul_u32_u24_e32 v4, 0x440, v1
	v_lshlrev_b32_e32 v184, 8, v1
	v_readlane_b32 s3, v255, 2
	v_add3_u32 v31, 0, v2, v21
	v_mov_b32_e32 v23, v185
	v_lshl_add_u64 v[24:25], s[2:3], 0, v[184:185]
	v_lshlrev_b32_e32 v26, 2, v0
	v_add_u32_e32 v40, v3, v4
	v_add_u32_e32 v106, 0x1100, v40
	v_readlane_b32 s0, v253, 22
	s_mov_b32 s7, s71
	s_branch .LBB0_1431

; #define LAS __attribute__((address_space(3)))
; #define CARRY_LOAD(Q, C) do { const float* pc_ = PC + cb0 + (size_t)(C) * 4096 + g4 * 64 + ct * 16 + fr; \
;                 _Pragma("unroll") for (int kk = 0; kk < 16; ++kk) pr[Q][kk] = pc_[kk * 256]; \
;                 const float* lc_ = LC + cb0 + (size_t)(C) * 4096 + (size_t)(r0 + g4 * 4) * 64 + ct * 16 + fr; \
;                 lr[Q] = (f32x4c){lc_[0], lc_[64], lc_[128], lc_[192]}; } while (0)
; __device__ __forceinline__ void even_carry(const Params& p, int j, LAS unsigned char* lds, const int wave_s) {
;     ...
;             CARRY_LOAD(0, 0); CARRY_LOAD(1, 1); CARRY_LOAD(2, 2); CARRY_LOAD(3, 3);
;             f32x4c d = (f32x4c){0.f, 0.f, 0.f, 0.f};
;             for (int c4 = 0; c4 < NCH; c4 += 4) {
; #pragma unroll
;                 for (int q = 0; q < 4; ++q) {
;                     const int c = c4 + q;
;                     float* sst = SST + cb0 + (size_t)c * 4096 + (size_t)(r0 + g4 * 4) * 64 + ct * 16 + fr;
;                     LAS float* sb = Ss + (c & 1) * 1024;
; #pragma unroll
;                     for (int r = 0; r < 4; ++r) { sst[r * 64] = d[r]; sb[(g4 * 4 + r) * 64 + ct * 16 + fr] = d[r]; }
;                     __syncthreads();
;                     f32x4c acc = lr[q];
; #pragma unroll
;                     for (int kk = 0; kk < 16; ++kk) acc = __builtin_amdgcn_mfma_f32_16x16x4f32(sb[fr * 64 + kk * 4 + g4], pr[q][kk], acc, 0, 0, 0);
;                     d = acc;
;                     if (c + 4 < NCH) CARRY_LOAD(q, c + 4);
.LBB0_1436:
	v_lshl_add_u64 v[36:37], v[34:35], 0, v[22:23]
	s_mov_b32 s2, 0x3db00000
	v_add_co_u32_e32 v38, vcc, s2, v36
	s_cmp_lt_u32 s24, 28
	s_nop 0
	v_addc_co_u32_e32 v39, vcc, 0, v37, vcc
	global_store_dword v[38:39], v16, off
	global_store_dword v[38:39], v17, off offset:256
	ds_write2_b32 v40, v16, v17 offset1:68
	global_store_dword v[38:39], v18, off offset:512
	global_store_dword v[38:39], v19, off offset:768
	ds_write2_b32 v40, v18, v19 offset0:136 offset1:204
	s_waitcnt lgkmcnt(0)
	s_barrier
	ds_read2_b32 v[38:39], v31 offset1:4
	s_waitcnt vmcnt(16) lgkmcnt(0)
	v_mfma_f32_16x16x4_f32 v[16:19], v38, v27, v[0:3]
	s_cselect_b64 s[12:13], -1, 0
	s_cmp_gt_u32 s24, 27
	s_cselect_b64 s[2:3], -1, 0
	s_and_b64 vcc, exec, s[2:3]
	v_mfma_f32_16x16x4_f32 v[16:19], v39, v41, v[16:19]
	ds_read2_b32 v[38:39], v31 offset0:8 offset1:12
	s_waitcnt lgkmcnt(0)
	v_mfma_f32_16x16x4_f32 v[16:19], v38, v42, v[16:19]
	v_mfma_f32_16x16x4_f32 v[16:19], v39, v43, v[16:19]
	ds_read2_b32 v[38:39], v31 offset0:16 offset1:20
	s_waitcnt lgkmcnt(0)
	v_mfma_f32_16x16x4_f32 v[16:19], v38, v44, v[16:19]
	v_mfma_f32_16x16x4_f32 v[16:19], v39, v45, v[16:19]
	ds_read2_b32 v[38:39], v31 offset0:24 offset1:28
	s_waitcnt lgkmcnt(0)
	v_mfma_f32_16x16x4_f32 v[16:19], v38, v46, v[16:19]
	v_mfma_f32_16x16x4_f32 v[16:19], v39, v47, v[16:19]
	ds_read2_b32 v[38:39], v31 offset0:32 offset1:36
	s_waitcnt lgkmcnt(0)
	v_mfma_f32_16x16x4_f32 v[16:19], v38, v48, v[16:19]
	v_mfma_f32_16x16x4_f32 v[16:19], v39, v49, v[16:19]
	ds_read2_b32 v[38:39], v31 offset0:40 offset1:44
	s_waitcnt lgkmcnt(0)
	v_mfma_f32_16x16x4_f32 v[16:19], v38, v50, v[16:19]
	v_mfma_f32_16x16x4_f32 v[16:19], v39, v51, v[16:19]
	ds_read2_b32 v[38:39], v31 offset0:48 offset1:52
	s_waitcnt lgkmcnt(0)
	v_mfma_f32_16x16x4_f32 v[16:19], v38, v52, v[16:19]
	v_mfma_f32_16x16x4_f32 v[16:19], v39, v53, v[16:19]
	ds_read2_b32 v[38:39], v31 offset0:56 offset1:60
	s_waitcnt lgkmcnt(0)
	v_mfma_f32_16x16x4_f32 v[16:19], v38, v54, v[16:19]
	v_mfma_f32_16x16x4_f32 v[16:19], v39, v55, v[16:19]
	v_lshl_add_u64 v[38:39], v[32:33], 0, v[22:23]
	s_cbranch_vccnz .LBB0_1438
	v_add_co_u32_e32 v0, vcc, 0x3b910000, v38
	s_nop 1
	v_addc_co_u32_e32 v1, vcc, 0, v39, vcc
	v_add_co_u32_e32 v2, vcc, 0x3b911000, v38
	s_nop 1
	v_addc_co_u32_e32 v3, vcc, 0, v39, vcc
	global_load_dword v27, v[0:1], off
	global_load_dword v41, v[0:1], off offset:1024
	global_load_dword v42, v[0:1], off offset:2048
	global_load_dword v43, v[0:1], off offset:3072
	global_load_dword v44, v[2:3], off
	global_load_dword v45, v[2:3], off offset:1024
	global_load_dword v46, v[2:3], off offset:2048
	global_load_dword v47, v[2:3], off offset:3072
	v_add_co_u32_e32 v0, vcc, 0x3b912000, v38
	s_nop 1
	v_addc_co_u32_e32 v1, vcc, 0, v39, vcc
	v_add_co_u32_e32 v2, vcc, 0x3b913000, v38
	s_nop 1
	v_addc_co_u32_e32 v3, vcc, 0, v39, vcc
	global_load_dword v48, v[0:1], off
	global_load_dword v49, v[0:1], off offset:1024
	global_load_dword v50, v[0:1], off offset:2048
	global_load_dword v51, v[0:1], off offset:3072
	global_load_dword v52, v[2:3], off
	global_load_dword v53, v[2:3], off offset:1024
	global_load_dword v54, v[2:3], off offset:2048
	global_load_dword v55, v[2:3], off offset:3072
	v_add_co_u32_e32 v104, vcc, 0x39710000, v36
	s_nop 1
	v_addc_co_u32_e32 v105, vcc, 0, v37, vcc
	global_load_dword v0, v[104:105], off
	global_load_dword v1, v[104:105], off offset:256
	global_load_dword v2, v[104:105], off offset:512
	global_load_dword v3, v[104:105], off offset:768
.LBB0_1438:
	s_mov_b32 s25, 0x3db04000
	v_add_co_u32_e32 v104, vcc, s25, v36
	v_add_u32_e32 v103, 0x1100, v31
	s_nop 0
	v_addc_co_u32_e32 v105, vcc, 0, v37, vcc
	s_nop 2
	global_store_dword v[104:105], v16, off
	global_store_dword v[104:105], v17, off offset:256
	ds_write2_b32 v106, v16, v17 offset1:68
	global_store_dword v[104:105], v18, off offset:512
	global_store_dword v[104:105], v19, off offset:768
	ds_write2_b32 v106, v18, v19 offset0:136 offset1:204
	s_waitcnt lgkmcnt(0)
	s_barrier
	ds_read2_b32 v[104:105], v103 offset1:4
	s_waitcnt vmcnt(16) lgkmcnt(0)
	v_mfma_f32_16x16x4_f32 v[16:19], v104, v29, v[4:7]
	s_andn2_b64 vcc, exec, s[12:13]
	v_mfma_f32_16x16x4_f32 v[16:19], v105, v56, v[16:19]
	ds_read2_b32 v[104:105], v103 offset0:8 offset1:12
	s_waitcnt lgkmcnt(0)
	v_mfma_f32_16x16x4_f32 v[16:19], v104, v57, v[16:19]
	v_mfma_f32_16x16x4_f32 v[16:19], v105, v58, v[16:19]
	ds_read2_b32 v[104:105], v103 offset0:16 offset1:20
	s_waitcnt lgkmcnt(0)
	v_mfma_f32_16x16x4_f32 v[16:19], v104, v59, v[16:19]
	v_mfma_f32_16x16x4_f32 v[16:19], v105, v60, v[16:19]
	ds_read2_b32 v[104:105], v103 offset0:24 offset1:28
	s_waitcnt lgkmcnt(0)
	v_mfma_f32_16x16x4_f32 v[16:19], v104, v61, v[16:19]
	v_mfma_f32_16x16x4_f32 v[16:19], v105, v62, v[16:19]
	ds_read2_b32 v[104:105], v103 offset0:32 offset1:36
	s_waitcnt lgkmcnt(0)
	v_mfma_f32_16x16x4_f32 v[16:19], v104, v63, v[16:19]
	v_mfma_f32_16x16x4_f32 v[16:19], v105, v64, v[16:19]
	ds_read2_b32 v[104:105], v103 offset0:40 offset1:44
	s_waitcnt lgkmcnt(0)
	v_mfma_f32_16x16x4_f32 v[16:19], v104, v65, v[16:19]
	v_mfma_f32_16x16x4_f32 v[16:19], v105, v66, v[16:19]
	ds_read2_b32 v[104:105], v103 offset0:48 offset1:52
	s_waitcnt lgkmcnt(0)
	v_mfma_f32_16x16x4_f32 v[16:19], v104, v67, v[16:19]
	v_mfma_f32_16x16x4_f32 v[16:19], v105, v68, v[16:19]
	ds_read2_b32 v[104:105], v103 offset0:56 offset1:60
	s_waitcnt lgkmcnt(0)
	v_mfma_f32_16x16x4_f32 v[16:19], v104, v69, v[16:19]
	v_cndmask_b32_e64 v104, 0, 1, s[12:13]
	v_cmp_ne_u32_e64 s[38:39], 1, v104
	v_mfma_f32_16x16x4_f32 v[16:19], v105, v70, v[16:19]
	s_cbranch_vccnz .LBB0_1440
	v_add_co_u32_e32 v4, vcc, 0x3b914000, v38
	s_nop 1
	v_addc_co_u32_e32 v5, vcc, 0, v39, vcc
	v_add_co_u32_e32 v6, vcc, 0x3b915000, v38
	s_nop 1
	v_addc_co_u32_e32 v7, vcc, 0, v39, vcc
	global_load_dword v29, v[4:5], off
	global_load_dword v56, v[4:5], off offset:1024
	global_load_dword v57, v[4:5], off offset:2048
	global_load_dword v58, v[4:5], off offset:3072
	global_load_dword v59, v[6:7], off
	global_load_dword v60, v[6:7], off offset:1024
	global_load_dword v61, v[6:7], off offset:2048
	global_load_dword v62, v[6:7], off offset:3072
	v_add_co_u32_e32 v4, vcc, 0x3b916000, v38
	s_nop 1
	v_addc_co_u32_e32 v5, vcc, 0, v39, vcc
	v_add_co_u32_e32 v6, vcc, 0x3b917000, v38
	s_nop 1
	v_addc_co_u32_e32 v7, vcc, 0, v39, vcc
	global_load_dword v63, v[4:5], off
	global_load_dword v64, v[4:5], off offset:1024
	global_load_dword v65, v[4:5], off offset:2048
	global_load_dword v66, v[4:5], off offset:3072
	global_load_dword v67, v[6:7], off
	global_load_dword v68, v[6:7], off offset:1024
	global_load_dword v69, v[6:7], off offset:2048
	global_load_dword v70, v[6:7], off offset:3072
	v_add_co_u32_e32 v104, vcc, 0x39714000, v36
	s_nop 1
	v_addc_co_u32_e32 v105, vcc, 0, v37, vcc
	global_load_dword v4, v[104:105], off
	global_load_dword v5, v[104:105], off offset:256
	global_load_dword v6, v[104:105], off offset:512
	global_load_dword v7, v[104:105], off offset:768
; #define LAS __attribute__((address_space(3)))
; #define CARRY_LOAD(Q, C) do { const float* pc_ = PC + cb0 + (size_t)(C) * 4096 + g4 * 64 + ct * 16 + fr; \
;                 _Pragma("unroll") for (int kk = 0; kk < 16; ++kk) pr[Q][kk] = pc_[kk * 256]; \
;                 const float* lc_ = LC + cb0 + (size_t)(C) * 4096 + (size_t)(r0 + g4 * 4) * 64 + ct * 16 + fr; \
;                 lr[Q] = (f32x4c){lc_[0], lc_[64], lc_[128], lc_[192]}; } while (0)
; __device__ __forceinline__ void even_carry(const Params& p, int j, LAS unsigned char* lds, const int wave_s) {
;     ...
;             CARRY_LOAD(0, 0); CARRY_LOAD(1, 1); CARRY_LOAD(2, 2); CARRY_LOAD(3, 3);
;             f32x4c d = (f32x4c){0.f, 0.f, 0.f, 0.f};
;             for (int c4 = 0; c4 < NCH; c4 += 4) {
; #pragma unroll
;                 for (int q = 0; q < 4; ++q) {
;                     const int c = c4 + q;
;                     float* sst = SST + cb0 + (size_t)c * 4096 + (size_t)(r0 + g4 * 4) * 64 + ct * 16 + fr;
;                     LAS float* sb = Ss + (c & 1) * 1024;
; #pragma unroll
;                     for (int r = 0; r < 4; ++r) { sst[r * 64] = d[r]; sb[(g4 * 4 + r) * 64 + ct * 16 + fr] = d[r]; }
;                     __syncthreads();
;                     f32x4c acc = lr[q];
; #pragma unroll
;                     for (int kk = 0; kk < 16; ++kk) acc = __builtin_amdgcn_mfma_f32_16x16x4f32(sb[fr * 64 + kk * 4 + g4], pr[q][kk], acc, 0, 0, 0);
;                     d = acc;
;                     if (c + 4 < NCH) CARRY_LOAD(q, c + 4);
.LBB0_1440:
	s_mov_b32 s12, 0x3db08000
	v_add_co_u32_e32 v104, vcc, s12, v36
	s_nop 1
	v_addc_co_u32_e32 v105, vcc, 0, v37, vcc
	s_nop 3
	global_store_dword v[104:105], v16, off
	global_store_dword v[104:105], v17, off offset:256
	ds_write2_b32 v40, v16, v17 offset1:68
	global_store_dword v[104:105], v18, off offset:512
	global_store_dword v[104:105], v19, off offset:768
	ds_write2_b32 v40, v18, v19 offset0:136 offset1:204
	s_waitcnt lgkmcnt(0)
	s_barrier
	ds_read2_b32 v[104:105], v31 offset1:4
	s_waitcnt vmcnt(16) lgkmcnt(0)
	v_mfma_f32_16x16x4_f32 v[16:19], v104, v71, v[8:11]
	s_and_b64 vcc, exec, s[38:39]
	v_mfma_f32_16x16x4_f32 v[16:19], v105, v72, v[16:19]
	ds_read2_b32 v[104:105], v31 offset0:8 offset1:12
	s_waitcnt lgkmcnt(0)
	v_mfma_f32_16x16x4_f32 v[16:19], v104, v73, v[16:19]
	v_mfma_f32_16x16x4_f32 v[16:19], v105, v74, v[16:19]
	ds_read2_b32 v[104:105], v31 offset0:16 offset1:20
	s_waitcnt lgkmcnt(0)
	v_mfma_f32_16x16x4_f32 v[16:19], v104, v75, v[16:19]
	v_mfma_f32_16x16x4_f32 v[16:19], v105, v76, v[16:19]
	ds_read2_b32 v[104:105], v31 offset0:24 offset1:28
	s_waitcnt lgkmcnt(0)
	v_mfma_f32_16x16x4_f32 v[16:19], v104, v77, v[16:19]
	v_mfma_f32_16x16x4_f32 v[16:19], v105, v78, v[16:19]
	ds_read2_b32 v[104:105], v31 offset0:32 offset1:36
	s_waitcnt lgkmcnt(0)
	v_mfma_f32_16x16x4_f32 v[16:19], v104, v79, v[16:19]
	v_mfma_f32_16x16x4_f32 v[16:19], v105, v80, v[16:19]
	ds_read2_b32 v[104:105], v31 offset0:40 offset1:44
	s_waitcnt lgkmcnt(0)
	v_mfma_f32_16x16x4_f32 v[16:19], v104, v81, v[16:19]
	v_mfma_f32_16x16x4_f32 v[16:19], v105, v82, v[16:19]
	ds_read2_b32 v[104:105], v31 offset0:48 offset1:52
	s_waitcnt lgkmcnt(0)
	v_mfma_f32_16x16x4_f32 v[16:19], v104, v86, v[16:19]
	v_mfma_f32_16x16x4_f32 v[16:19], v105, v88, v[16:19]
	ds_read2_b32 v[104:105], v31 offset0:56 offset1:60
	s_waitcnt lgkmcnt(0)
	v_mfma_f32_16x16x4_f32 v[16:19], v104, v89, v[16:19]
	v_mfma_f32_16x16x4_f32 v[16:19], v105, v90, v[16:19]
	s_cbranch_vccnz .LBB0_1442
	v_add_co_u32_e32 v8, vcc, 0x3b918000, v38
	s_nop 1
	v_addc_co_u32_e32 v9, vcc, 0, v39, vcc
	v_add_co_u32_e32 v10, vcc, 0x3b919000, v38
	s_nop 1
	v_addc_co_u32_e32 v11, vcc, 0, v39, vcc
	global_load_dword v71, v[8:9], off
	global_load_dword v72, v[8:9], off offset:1024
	global_load_dword v73, v[8:9], off offset:2048
	global_load_dword v74, v[8:9], off offset:3072
	global_load_dword v75, v[10:11], off
	global_load_dword v76, v[10:11], off offset:1024
	global_load_dword v77, v[10:11], off offset:2048
	global_load_dword v78, v[10:11], off offset:3072
	v_add_co_u32_e32 v8, vcc, 0x3b91a000, v38
	s_nop 1
	v_addc_co_u32_e32 v9, vcc, 0, v39, vcc
	v_add_co_u32_e32 v10, vcc, 0x3b91b000, v38
	s_nop 1
	v_addc_co_u32_e32 v11, vcc, 0, v39, vcc
	global_load_dword v79, v[8:9], off
	global_load_dword v80, v[8:9], off offset:1024
	global_load_dword v81, v[8:9], off offset:2048
	global_load_dword v82, v[8:9], off offset:3072
	global_load_dword v86, v[10:11], off
	global_load_dword v88, v[10:11], off offset:1024
	global_load_dword v89, v[10:11], off offset:2048
	global_load_dword v90, v[10:11], off offset:3072
	v_add_co_u32_e32 v104, vcc, 0x39718000, v36
	s_nop 1
	v_addc_co_u32_e32 v105, vcc, 0, v37, vcc
	global_load_dword v8, v[104:105], off
	global_load_dword v9, v[104:105], off offset:256
	global_load_dword v10, v[104:105], off offset:512
	global_load_dword v11, v[104:105], off offset:768
.LBB0_1442:
	s_mov_b32 s12, 0x3db0c000
	v_add_co_u32_e32 v104, vcc, s12, v36
	s_nop 1
	v_addc_co_u32_e32 v105, vcc, 0, v37, vcc
	s_nop 3
	global_store_dword v[104:105], v16, off
	global_store_dword v[104:105], v17, off offset:256
	ds_write2_b32 v106, v16, v17 offset1:68
	global_store_dword v[104:105], v18, off offset:512
	global_store_dword v[104:105], v19, off offset:768
	ds_write2_b32 v106, v18, v19 offset0:136 offset1:204
	s_waitcnt lgkmcnt(0)
	s_barrier
	ds_read2_b32 v[104:105], v103 offset1:4
	s_waitcnt vmcnt(16) lgkmcnt(0)
	v_mfma_f32_16x16x4_f32 v[16:19], v104, v83, v[12:15]
	s_and_b64 vcc, exec, s[38:39]
	v_mfma_f32_16x16x4_f32 v[16:19], v105, v84, v[16:19]
	ds_read2_b32 v[104:105], v103 offset0:8 offset1:12
	s_waitcnt lgkmcnt(0)
	v_mfma_f32_16x16x4_f32 v[16:19], v104, v85, v[16:19]
	v_mfma_f32_16x16x4_f32 v[16:19], v105, v87, v[16:19]
	ds_read2_b32 v[104:105], v103 offset0:16 offset1:20
	s_waitcnt lgkmcnt(0)
	v_mfma_f32_16x16x4_f32 v[16:19], v104, v91, v[16:19]
	v_mfma_f32_16x16x4_f32 v[16:19], v105, v92, v[16:19]
	ds_read2_b32 v[104:105], v103 offset0:24 offset1:28
	s_waitcnt lgkmcnt(0)
	v_mfma_f32_16x16x4_f32 v[16:19], v104, v93, v[16:19]
	v_mfma_f32_16x16x4_f32 v[16:19], v105, v94, v[16:19]
	ds_read2_b32 v[104:105], v103 offset0:32 offset1:36
	s_waitcnt lgkmcnt(0)
	v_mfma_f32_16x16x4_f32 v[16:19], v104, v95, v[16:19]
	v_mfma_f32_16x16x4_f32 v[16:19], v105, v96, v[16:19]
	ds_read2_b32 v[104:105], v103 offset0:40 offset1:44
	s_waitcnt lgkmcnt(0)
	v_mfma_f32_16x16x4_f32 v[16:19], v104, v97, v[16:19]
	v_mfma_f32_16x16x4_f32 v[16:19], v105, v98, v[16:19]
	ds_read2_b32 v[104:105], v103 offset0:48 offset1:52
	s_waitcnt lgkmcnt(0)
	v_mfma_f32_16x16x4_f32 v[16:19], v104, v99, v[16:19]
	v_mfma_f32_16x16x4_f32 v[16:19], v105, v100, v[16:19]
	ds_read2_b32 v[104:105], v103 offset0:56 offset1:60
	s_waitcnt lgkmcnt(0)
	v_mfma_f32_16x16x4_f32 v[16:19], v104, v101, v[16:19]
	v_mfma_f32_16x16x4_f32 v[16:19], v105, v102, v[16:19]
	s_cbranch_vccnz .LBB0_1435
	v_add_co_u32_e32 v12, vcc, 0x3b91c000, v38
	s_nop 1
	v_addc_co_u32_e32 v13, vcc, 0, v39, vcc
	global_load_dword v83, v[12:13], off
	global_load_dword v84, v[12:13], off offset:1024
	global_load_dword v85, v[12:13], off offset:2048
	global_load_dword v87, v[12:13], off offset:3072
	v_add_co_u32_e32 v12, vcc, 0x3b91d000, v38
	s_nop 1
	v_addc_co_u32_e32 v13, vcc, 0, v39, vcc
	global_load_dword v91, v[12:13], off
	global_load_dword v92, v[12:13], off offset:1024
	global_load_dword v93, v[12:13], off offset:2048
	global_load_dword v94, v[12:13], off offset:3072
	v_add_co_u32_e32 v12, vcc, 0x3b91e000, v38
	s_nop 1
	v_addc_co_u32_e32 v13, vcc, 0, v39, vcc
	global_load_dword v95, v[12:13], off
	global_load_dword v96, v[12:13], off offset:1024
	global_load_dword v97, v[12:13], off offset:2048
	global_load_dword v98, v[12:13], off offset:3072
	v_add_co_u32_e32 v12, vcc, 0x3b91f000, v38
	s_nop 1
	v_addc_co_u32_e32 v13, vcc, 0, v39, vcc
	v_add_co_u32_e32 v36, vcc, 0x3971c000, v36
	global_load_dword v99, v[12:13], off
	global_load_dword v100, v[12:13], off offset:1024
	global_load_dword v101, v[12:13], off offset:2048
	global_load_dword v102, v[12:13], off offset:3072
	v_addc_co_u32_e32 v37, vcc, 0, v37, vcc
	global_load_dword v12, v[36:37], off
	global_load_dword v13, v[36:37], off offset:256
	global_load_dword v14, v[36:37], off offset:512
	global_load_dword v15, v[36:37], off offset:768
	s_branch .LBB0_1435
